# layer-3 S5 in-proj weight conversion moved to the leading half (its phase-12 tail), off the lagging half's critical path; lagging half waits on generation 11
# speedup vs baseline: 1.0314x; 1.0012x over previous
.LBB0_151:
	v_readlane_b32 s100, v255, 61
	s_nop 0
	s_cmp_eq_u32 s100, 0
	s_cselect_b32 s100, 4, 12
	s_cmp_lg_u32 s54, s100
	s_cbranch_scc1 .Lxw_done
.Lxw:
	v_readfirstlane_b32 s100, v247
	s_nop 3
	s_cmp_ge_u32 s100, 64
	s_cbranch_scc1 .Lxw_join
	v_readlane_b32 s100, v255, 61
	s_load_dwordx2 s[98:99], s[66:67], 0xb0
	s_sub_i32 s101, 2, s100
	s_mul_i32 s101, s101, 0x3600
	s_add_i32 s101, s101, 0x8563500
	s_waitcnt lgkmcnt(0)
	s_add_u32 s98, s98, s101
	s_addc_u32 s99, s99, 0
	s_cmp_eq_u32 s100, 0
	s_cselect_b32 s101, 1, 11
	s_mov_b32 s100, 0x2000

.LBB0_931:
	v_readlane_b32 s4, v255, 61
	s_mov_b64 s[2:3], -1
	s_cmp_eq_u32 s4, 0
	s_cselect_b32 s4, 12, 1
	s_cmp_lg_u32 s54, s4
	s_cselect_b64 s[4:5], -1, 0
	s_andn2_b64 vcc, exec, s[4:5]
	s_mov_b64 s[4:5], 0
	s_cbranch_vccnz .LBB0_986

.LBB0_986:
	s_and_b64 vcc, exec, s[2:3]
	s_cbranch_vccz .LBB0_1001
	v_readlane_b32 s98, v255, 61
	s_nop 0
	s_cmp_eq_u32 s98, 0
	s_cselect_b32 s98, 0, 0x800
	s_movk_i32 s99, 0x1880
	s_cselect_b32 s99, 0x800, s99
	v_mov_b32_e32 v0, v247
	s_nop 0
	v_readfirstlane_b32 s2, v0
	s_ashr_i32 s4, s2, 6
	v_readlane_b32 s2, v253, 6
	s_add_i32 s14, s4, s2
	s_add_i32 s14, s14, s98
	s_cmp_ge_i32 s14, s99
	s_cbranch_scc1 .Lph4_bar
	s_load_dwordx2 s[2:3], s[88:89], 0x8
	v_lshlrev_b32_e32 v1, 2, v0
	s_mulk_i32 s4, 0x4100
	v_bfe_u32 v65, v0, 4, 2
	v_and_b32_e32 v64, 60, v1
	v_bfe_u32 v73, v0, 3, 3
	v_lshlrev_b32_e32 v0, 3, v0
	s_add_i32 s4, s4, 0
	v_lshlrev_b32_e32 v1, 2, v64
	v_mul_u32_u24_e32 v2, 0x104, v65
	v_and_b32_e32 v0, 56, v0
	v_add3_u32 v72, s4, v1, v2
	v_mul_u32_u24_e32 v1, 0x104, v0
	v_lshlrev_b32_e32 v2, 2, v73
	v_add3_u32 v74, s4, v1, v2
	s_waitcnt lgkmcnt(0)
	s_add_u32 s4, s2, 0x4000
	v_lshlrev_b32_e32 v208, 1, v0
	s_addc_u32 s5, s3, 0
	v_lshl_add_u64 v[2:3], s[82:83], 0, v[208:209]
	s_mov_b64 s[6:7], 0x4000000
	v_lshl_add_u64 v[66:67], v[2:3], 0, s[6:7]
	s_add_u32 s6, s2, 0x2000
	s_addc_u32 s7, s3, 0
	s_mov_b64 s[8:9], 0x2000000
	s_cmp_lg_u64 s[2:3], 0
	v_or_b32_e32 v75, 8, v73
	v_or_b32_e32 v76, 16, v73
	v_or_b32_e32 v77, 24, v73
	v_or_b32_e32 v78, 32, v73
	v_or_b32_e32 v79, 40, v73
	v_or_b32_e32 v80, 48, v73
	v_or_b32_e32 v81, 56, v73
	v_lshl_add_u64 v[68:69], v[2:3], 0, s[8:9]
	s_cselect_b64 s[8:9], -1, 0
	v_lshlrev_b32_e32 v70, 1, v0
	s_branch .LBB0_992
